# c22 + P12 conv/silu epilogue output stores widened: the two 8-byte halves a lane owns (sections 1+3, 2+4) written as one dwordx4; 16 dwordx2 -> 8 dwordx4 per wave-tile, same bytes
# speedup vs baseline: 1.0060x; 1.0060x over previous
;     __device__ __forceinline__ void operator()(const f32x4 (&acc)[2][2][4][2], const Unit& u, int wr, int wc, int fr, int fq) const {
;     ...
;             const f32x4 wg0 = *(const f32x4*)(cw + ch0 + 4 * n), wg1 = *(const f32x4*)(cw + 5632 + ch0 + 4 * n), wg2 = *(const f32x4*)(cw + 2 * 5632 + ch0 + 4 * n), bg = *(const f32x4*)(cb + ch0 + 4 * n);
;             const f32x4 wv0 = *(const f32x4*)(cw + 2816 + ch0 + 4 * n), wv1 = *(const f32x4*)(cw + 5632 + 2816 + ch0 + 4 * n), wv2 = *(const f32x4*)(cw + 2 * 5632 + 2816 + ch0 + 4 * n), bv = *(const f32x4*)(cb + 2816 + ch0 + 4 * n);
; #pragma unroll
;             for (int ai = 0; ai < 2; ++ai) {
;                 const int stripe = u.pm * 4 + ai * 2 + wr;
;                 f32x4 pg1, pg2, pv1, pv2;
; #pragma unroll
;                 for (int e = 0; e < 4; ++e) { pg1[e] = dpp_shr1(acc[ai][0][3][n][e]); pg2[e] = dpp_shr1(acc[ai][0][2][n][e]); pv1[e] = dpp_shr1(acc[ai][1][3][n][e]); pv2[e] = dpp_shr1(acc[ai][1][2][n][e]); }
;                 f32x4 yg[4], yv[4];
;                 yg[0] = bg + wg0 * pg2 + wg1 * pg1 + wg2 * acc[ai][0][0][n];
;                 yg[1] = bg + wg0 * pg1 + wg1 * acc[ai][0][0][n] + wg2 * acc[ai][0][1][n];
;                 yg[2] = bg + wg0 * acc[ai][0][0][n] + wg1 * acc[ai][0][1][n] + wg2 * acc[ai][0][2][n];
;                 yg[3] = bg + wg0 * acc[ai][0][1][n] + wg1 * acc[ai][0][2][n] + wg2 * acc[ai][0][3][n];
;                 yv[0] = bv + wv0 * pv2 + wv1 * pv1 + wv2 * acc[ai][1][0][n];
;                 yv[1] = bv + wv0 * pv1 + wv1 * acc[ai][1][0][n] + wv2 * acc[ai][1][1][n];
;                 yv[2] = bv + wv0 * acc[ai][1][0][n] + wv1 * acc[ai][1][1][n] + wv2 * acc[ai][1][2][n];
;                 yv[3] = bv + wv0 * acc[ai][1][1][n] + wv1 * acc[ai][1][2][n] + wv2 * acc[ai][1][3][n];
;                 bf16_t* arow = act + (size_t)(stripe * 64 + 4 * fr) * 2816 + ch0 + 4 * n;
; #pragma unroll
;                 for (int m = 0; m < 4; ++m) { f32x4 o;
; #pragma unroll
;                     for (int e = 0; e < 4; ++e) o[e] = yg[m][e] * __builtin_amdgcn_rcpf(1.0f + __expf(-yg[m][e])) * yv[m][e];
;                     *(unsigned long long*)(arow + (size_t)m * 2816) = (unsigned long long)cvt_pk_bf16(o[0], o[1]) | ((unsigned long long)cvt_pk_bf16(o[2], o[3]) << 32); }
.LBB0_1318:
	v_lshl_or_b32 v190, s88, 7, v193
	v_ashrrev_i32_e32 v191, 31, v190
	v_lshlrev_b64 v[140:141], 2, v[190:191]
	v_lshl_add_u64 v[182:183], s[44:45], 0, v[140:141]
	v_lshl_add_u64 v[184:185], s[46:47], 0, v[140:141]
	global_load_dwordx4 v[144:147], v[182:183], off
	global_load_dwordx4 v[148:151], v[184:185], off
	v_lshl_add_u64 v[128:129], s[26:27], 0, v[140:141]
	v_lshl_add_u64 v[132:133], s[40:41], 0, v[140:141]
	v_lshl_add_u64 v[136:137], s[20:21], 0, v[140:141]
	global_load_dwordx4 v[128:131], v[128:129], off
	s_nop 0
	global_load_dwordx4 v[132:135], v[132:133], off
	v_lshl_add_u64 v[142:143], s[22:23], 0, v[140:141]
	global_load_dwordx4 v[152:155], v[136:137], off
	global_load_dwordx4 v[156:159], v[142:143], off
	v_lshl_add_u64 v[136:137], s[36:37], 0, v[140:141]
	global_load_dwordx4 v[136:139], v[136:137], off
	v_lshl_add_u64 v[140:141], s[38:39], 0, v[140:141]
	global_load_dwordx4 v[140:143], v[140:141], off
	v_mov_b32_dpp v186, v120 row_shr:1 row_mask:0xf bank_mask:0xf bound_ctrl:1
	v_mov_b32_dpp v187, v121 row_shr:1 row_mask:0xf bank_mask:0xf bound_ctrl:1
	s_lshl_b32 s3, s6, 2
	v_mov_b32_dpp v178, v108 row_shr:1 row_mask:0xf bank_mask:0xf bound_ctrl:1
	v_mov_b32_dpp v179, v109 row_shr:1 row_mask:0xf bank_mask:0xf bound_ctrl:1
	s_add_i32 s58, s3, s64
	v_mov_b64_e32 v[180:181], s[12:13]
	v_lshl_or_b32 v199, s58, 6, v194
	v_mad_i64_i32 v[180:181], s[6:7], v199, s81, v[180:181]
	v_mov_b32_dpp v202, v110 row_shr:1 row_mask:0xf bank_mask:0xf bound_ctrl:1
	v_mov_b32_dpp v203, v111 row_shr:1 row_mask:0xf bank_mask:0xf bound_ctrl:1
	v_mov_b32_dpp v200, v104 row_shr:1 row_mask:0xf bank_mask:0xf bound_ctrl:1
	v_mov_b32_dpp v201, v105 row_shr:1 row_mask:0xf bank_mask:0xf bound_ctrl:1
	v_mov_b32_dpp v204, v122 row_shr:1 row_mask:0xf bank_mask:0xf bound_ctrl:1
	v_mov_b32_dpp v205, v123 row_shr:1 row_mask:0xf bank_mask:0xf bound_ctrl:1
	v_mov_b32_dpp v188, v96 row_shr:1 row_mask:0xf bank_mask:0xf bound_ctrl:1
	v_mov_b32_dpp v189, v97 row_shr:1 row_mask:0xf bank_mask:0xf bound_ctrl:1
	v_mov_b32_dpp v208, v106 row_shr:1 row_mask:0xf bank_mask:0xf bound_ctrl:1
	v_mov_b32_dpp v209, v107 row_shr:1 row_mask:0xf bank_mask:0xf bound_ctrl:1
	v_mov_b32_dpp v206, v98 row_shr:1 row_mask:0xf bank_mask:0xf bound_ctrl:1
	v_mov_b32_dpp v207, v99 row_shr:1 row_mask:0xf bank_mask:0xf bound_ctrl:1
	v_lshl_add_u64 v[180:181], v[190:191], 1, v[180:181]
	s_mov_b64 s[8:9], -1
	s_waitcnt vmcnt(0)
	v_pk_fma_f32 v[186:187], v[144:145], v[186:187], v[148:149]
	v_pk_fma_f32 v[212:213], v[144:145], v[178:179], v[148:149]
	v_pk_fma_f32 v[210:211], v[146:147], v[202:203], v[150:151]
	v_pk_fma_f32 v[214:215], v[126:127], v[146:147], v[150:151]
	v_pk_fma_f32 v[218:219], v[118:119], v[146:147], v[150:151]
	v_pk_fma_f32 v[226:227], v[114:115], v[130:131], v[134:135]
	v_pk_fma_f32 v[178:179], v[152:153], v[178:179], v[186:187]
	v_pk_fma_f32 v[186:187], v[126:127], v[154:155], v[210:211]
	v_pk_fma_f32 v[178:179], v[124:125], v[156:157], v[178:179]
	v_pk_fma_f32 v[210:211], v[118:119], v[154:155], v[214:215]
	v_mul_f32_e32 v199, 0xbfb8aa3b, v178
	v_exp_f32_e32 v199, v199
	v_pk_fma_f32 v[214:215], v[122:123], v[154:155], v[218:219]
	v_pk_fma_f32 v[218:219], v[102:103], v[138:139], v[226:227]
	v_mul_f32_e32 v226, 0xbfb8aa3b, v179
	v_add_f32_e32 v199, 1.0, v199
	v_exp_f32_e32 v226, v226
	v_rcp_f32_e32 v199, v199
	v_pk_fma_f32 v[204:205], v[146:147], v[204:205], v[150:151]
	v_pk_fma_f32 v[200:201], v[128:129], v[200:201], v[132:133]
	v_pk_fma_f32 v[224:225], v[128:129], v[188:189], v[132:133]
	v_pk_fma_f32 v[202:203], v[154:155], v[202:203], v[204:205]
	v_pk_fma_f32 v[188:189], v[136:137], v[188:189], v[200:201]
	v_pk_fma_f32 v[202:203], v[126:127], v[158:159], v[202:203]
	v_pk_fma_f32 v[188:189], v[112:113], v[140:141], v[188:189]
	v_add_f32_e32 v226, 1.0, v226
	v_mul_f32_e32 v178, v178, v199
	v_mul_f32_e32 v178, v188, v178
	v_rcp_f32_e32 v188, v226
	v_mul_f32_e32 v199, 0xbfb8aa3b, v202
	v_mul_f32_e32 v226, 0xbfb8aa3b, v203
	v_exp_f32_e32 v199, v199
	v_exp_f32_e32 v226, v226
	v_mul_f32_e32 v179, v179, v188
	v_pk_fma_f32 v[204:205], v[124:125], v[152:153], v[212:213]
	v_add_f32_e32 v188, 1.0, v199
	v_add_f32_e32 v199, 1.0, v226
	v_rcp_f32_e32 v199, v199
	v_pk_fma_f32 v[204:205], v[116:117], v[156:157], v[204:205]
	v_rcp_f32_e32 v188, v188
	v_mul_f32_e32 v179, v189, v179
	v_mul_f32_e32 v189, v203, v199
	v_mul_f32_e32 v199, 0xbfb8aa3b, v204
	v_pk_fma_f32 v[208:209], v[130:131], v[208:209], v[134:135]
	v_exp_f32_e32 v199, v199
	v_pk_fma_f32 v[222:223], v[130:131], v[206:207], v[134:135]
	v_pk_fma_f32 v[206:207], v[138:139], v[206:207], v[208:209]
	v_mul_f32_e32 v188, v202, v188
	v_pk_fma_f32 v[206:207], v[114:115], v[142:143], v[206:207]
	v_cvt_pk_bf16_f32 v178, v178, v179
	v_pk_fma_f32 v[186:187], v[118:119], v[158:159], v[186:187]
	v_mul_f32_e32 v188, v206, v188
	v_mul_f32_e32 v189, v207, v189
	v_cvt_pk_bf16_f32 v179, v188, v189
	v_add_f32_e32 v188, 1.0, v199
	v_rcp_f32_e32 v188, v188
	v_mul_f32_e32 v189, 0xbfb8aa3b, v205
	v_exp_f32_e32 v189, v189
	v_mov_b32_e32 v240, v178
	v_mov_b32_e32 v241, v179
	v_mul_f32_e32 v178, v204, v188
	v_mul_f32_e32 v188, 0xbfb8aa3b, v186
	v_add_f32_e32 v179, 1.0, v189
	v_exp_f32_e32 v188, v188
	v_mul_f32_e32 v189, 0xbfb8aa3b, v187
	v_exp_f32_e32 v189, v189
	v_rcp_f32_e32 v179, v179
	v_add_f32_e32 v188, 1.0, v188
	v_rcp_f32_e32 v188, v188
	v_add_f32_e32 v189, 1.0, v189
	v_rcp_f32_e32 v189, v189
	v_pk_fma_f32 v[216:217], v[124:125], v[144:145], v[148:149]
	v_pk_fma_f32 v[200:201], v[114:115], v[138:139], v[222:223]
	v_pk_fma_f32 v[208:209], v[112:113], v[136:137], v[224:225]
	v_pk_fma_f32 v[212:213], v[116:117], v[152:153], v[216:217]
; __device__ __forceinline__ unsigned cvt_pk_bf16(float lo, float hi) { unsigned r; asm volatile("v_cvt_pk_bf16_f32 %0, %1, %2" : "=v"(r) : "v"(lo), "v"(hi)); return r; }
;     __device__ __forceinline__ void operator()(const f32x4 (&acc)[2][2][4][2], const Unit& u, int wr, int wc, int fr, int fq) const {
;     ...
;                 bf16_t* arow = act + (size_t)(stripe * 64 + 4 * fr) * 2816 + ch0 + 4 * n;
; #pragma unroll
;                 for (int m = 0; m < 4; ++m) { f32x4 o;
; #pragma unroll
;                     for (int e = 0; e < 4; ++e) o[e] = yg[m][e] * __builtin_amdgcn_rcpf(1.0f + __expf(-yg[m][e])) * yv[m][e];
;                     *(unsigned long long*)(arow + (size_t)m * 2816) = (unsigned long long)cvt_pk_bf16(o[0], o[1]) | ((unsigned long long)cvt_pk_bf16(o[2], o[3]) << 32); }
;                 if (fr == 0 || fr == 15) {
;                     const int m0 = (fr == 0) ? 0 : 2;
; #pragma unroll
;                     for (int mm = 0; mm < 2; ++mm)
; #pragma unroll
;                         for (int bj = 0; bj < 2; ++bj) { const f32x4 x = (fr == 0) ? acc[ai][bj][mm][n] : acc[ai][bj][2 + mm][n];
;                             *(unsigned long long*)(edge + ((size_t)stripe * 4 + m0 + mm) * 5632 + ucol + bj * HALF + 4 * n) = (unsigned long long)cvt_pk_bf16(x[0], x[1]) | ((unsigned long long)cvt_pk_bf16(x[2], x[3]) << 32); }
	v_pk_fma_f32 v[200:201], v[102:103], v[142:143], v[200:201]
	v_pk_fma_f32 v[208:209], v[100:101], v[140:141], v[208:209]
	v_mul_f32_e32 v179, v205, v179
	v_mul_f32_e32 v186, v186, v188
	v_pk_fma_f32 v[212:213], v[120:121], v[156:157], v[212:213]
	v_mul_f32_e32 v178, v208, v178
	v_mul_f32_e32 v179, v209, v179
	v_mul_f32_e32 v186, v200, v186
	v_mul_f32_e32 v187, v187, v189
	v_mul_f32_e32 v187, v201, v187
	v_cvt_pk_bf16_f32 v178, v178, v179
	v_cvt_pk_bf16_f32 v179, v186, v187
	v_mul_f32_e32 v186, 0xbfb8aa3b, v212
	v_exp_f32_e32 v188, v186
	v_mul_f32_e32 v189, 0xbfb8aa3b, v213
	v_exp_f32_e32 v189, v189
	v_add_co_u32_e32 v186, vcc, s82, v180
	v_add_f32_e32 v188, 1.0, v188
	v_rcp_f32_e32 v188, v188
	v_pk_fma_f32 v[210:211], v[122:123], v[158:159], v[210:211]
	v_addc_co_u32_e32 v187, vcc, 0, v181, vcc
	v_mov_b32_e32 v242, v178
	v_mov_b32_e32 v243, v179
	v_mul_f32_e32 v178, v212, v188
	v_mul_f32_e32 v188, 0xbfb8aa3b, v210
	v_add_f32_e32 v179, 1.0, v189
	v_exp_f32_e32 v188, v188
	v_mul_f32_e32 v189, 0xbfb8aa3b, v211
	v_exp_f32_e32 v189, v189
	v_rcp_f32_e32 v179, v179
	v_add_f32_e32 v188, 1.0, v188
	v_rcp_f32_e32 v188, v188
	v_add_f32_e32 v189, 1.0, v189
	v_rcp_f32_e32 v189, v189
	v_pk_fma_f32 v[220:221], v[116:117], v[144:145], v[148:149]
	v_pk_fma_f32 v[228:229], v[112:113], v[128:129], v[132:133]
	v_pk_fma_f32 v[216:217], v[120:121], v[152:153], v[220:221]
	v_pk_fma_f32 v[220:221], v[100:101], v[136:137], v[228:229]
	v_pk_fma_f32 v[218:219], v[106:107], v[142:143], v[218:219]
	v_pk_fma_f32 v[220:221], v[104:105], v[140:141], v[220:221]
	v_mul_f32_e32 v179, v213, v179
	v_mul_f32_e32 v188, v210, v188
	v_pk_fma_f32 v[216:217], v[108:109], v[156:157], v[216:217]
	v_mul_f32_e32 v178, v220, v178
	v_mul_f32_e32 v179, v221, v179
	v_mul_f32_e32 v188, v218, v188
	v_mul_f32_e32 v189, v211, v189
	v_mul_f32_e32 v189, v219, v189
	v_cvt_pk_bf16_f32 v178, v178, v179
	v_cvt_pk_bf16_f32 v179, v188, v189
	v_mul_f32_e32 v188, 0xbfb8aa3b, v216
	v_exp_f32_e32 v199, v188
	v_mul_f32_e32 v200, 0xbfb8aa3b, v217
	v_exp_f32_e32 v200, v200
	v_add_co_u32_e32 v188, vcc, s72, v180
	v_add_f32_e32 v199, 1.0, v199
	v_rcp_f32_e32 v199, v199
	v_pk_fma_f32 v[214:215], v[110:111], v[158:159], v[214:215]
	v_addc_co_u32_e32 v189, vcc, 0, v181, vcc
	v_mov_b32_e32 v244, v178
	v_mov_b32_e32 v245, v179
	v_add_f32_e32 v179, 1.0, v200
	v_mul_f32_e32 v200, 0xbfb8aa3b, v215
	v_mul_f32_e32 v178, v216, v199
	v_mul_f32_e32 v199, 0xbfb8aa3b, v214
	v_exp_f32_e32 v200, v200
	v_exp_f32_e32 v199, v199
	v_rcp_f32_e32 v179, v179
	v_pk_fma_f32 v[230:231], v[102:103], v[130:131], v[134:135]
	v_add_f32_e32 v200, 1.0, v200
	v_add_f32_e32 v199, 1.0, v199
	v_rcp_f32_e32 v200, v200
	v_rcp_f32_e32 v199, v199
	v_pk_fma_f32 v[232:233], v[100:101], v[128:129], v[132:133]
	v_pk_fma_f32 v[222:223], v[106:107], v[138:139], v[230:231]
	v_pk_fma_f32 v[224:225], v[104:105], v[136:137], v[232:233]
	v_pk_fma_f32 v[222:223], v[98:99], v[142:143], v[222:223]
	v_pk_fma_f32 v[224:225], v[96:97], v[140:141], v[224:225]
	v_mul_f32_e32 v179, v217, v179
	v_mul_f32_e32 v200, v215, v200
	v_mul_f32_e32 v178, v224, v178
	v_mul_f32_e32 v179, v225, v179
	v_mul_f32_e32 v199, v214, v199
	v_mul_f32_e32 v200, v223, v200
	v_mul_f32_e32 v199, v222, v199
	v_cvt_pk_bf16_f32 v178, v178, v179
	v_cvt_pk_bf16_f32 v179, v199, v200
	v_add_co_u32_e32 v200, vcc, 0x4000, v180
	s_nop 1
	v_addc_co_u32_e32 v201, vcc, 0, v181, vcc
	v_cmp_gt_i32_e32 vcc, 15, v169
	v_mov_b32_e32 v246, v178
	v_mov_b32_e32 v247, v179
	s_and_saveexec_b64 s[6:7], vcc
	v_cmp_eq_u32_e32 vcc, 0, v169
	s_orn2_b64 s[8:9], vcc, exec
	s_or_b64 exec, exec, s[6:7]
	v_lshl_or_b32 v178, s88, 8, v193
	v_ashrrev_i32_e32 v179, 31, v178
	s_and_saveexec_b64 s[6:7], s[8:9]
	s_cbranch_execz .LBB0_1322
	s_ashr_i32 s59, s58, 31
	s_lshl_b64 s[8:9], s[58:59], 2
	v_cndmask_b32_e64 v122, v122, v126, s[0:1]
	v_cndmask_b32_e64 v123, v123, v127, s[0:1]
	v_cndmask_b32_e64 v120, v120, v124, s[0:1]
	v_cndmask_b32_e64 v121, v121, v125, s[0:1]
	v_or_b32_e32 v199, s8, v168
	v_cvt_pk_bf16_f32 v120, v120, v121
	v_cvt_pk_bf16_f32 v121, v122, v123
	v_mov_b64_e32 v[122:123], s[14:15]
	v_mad_u64_u32 v[122:123], s[28:29], v199, s83, v[122:123]
	v_mad_i32_i24 v123, s9, v198, v123
	v_lshl_add_u64 v[122:123], v[178:179], 1, v[122:123]
	v_cndmask_b32_e64 v104, v104, v112, s[0:1]
	v_cndmask_b32_e64 v105, v105, v113, s[0:1]
	global_store_dwordx2 v[122:123], v[120:121], off
	v_cndmask_b32_e64 v106, v106, v114, s[0:1]
	v_cndmask_b32_e64 v107, v107, v115, s[0:1]
	v_cvt_pk_bf16_f32 v104, v104, v105
	v_cvt_pk_bf16_f32 v105, v106, v107
	global_store_dwordx2 v[122:123], v[104:105], off offset:256
	v_cndmask_b32_e64 v105, v110, v118, s[0:1]
	v_cndmask_b32_e64 v106, v111, v119, s[0:1]
	v_cndmask_b32_e64 v104, v108, v116, s[0:1]
	v_cndmask_b32_e64 v107, v109, v117, s[0:1]
	v_add_co_u32_e32 v108, vcc, s72, v122
	v_cvt_pk_bf16_f32 v104, v104, v107
	v_cvt_pk_bf16_f32 v105, v105, v106
	v_lshl_add_u64 v[106:107], v[122:123], 0, s[24:25]
	s_nop 0
	v_addc_co_u32_e32 v109, vcc, 0, v123, vcc
	v_cndmask_b32_e64 v96, v96, v100, s[0:1]
	v_cndmask_b32_e64 v97, v97, v101, s[0:1]
	global_store_dwordx2 v[108:109], v[104:105], off offset:3072
	v_cndmask_b32_e64 v98, v98, v102, s[0:1]
	v_cndmask_b32_e64 v99, v99, v103, s[0:1]
	v_cvt_pk_bf16_f32 v96, v96, v97
	v_cvt_pk_bf16_f32 v97, v98, v99
	global_store_dwordx2 v[106:107], v[96:97], off offset:256
; __device__ __forceinline__ unsigned cvt_pk_bf16(float lo, float hi) { unsigned r; asm volatile("v_cvt_pk_bf16_f32 %0, %1, %2" : "=v"(r) : "v"(lo), "v"(hi)); return r; }
; __device__ __forceinline__ float dpp_shr1(float v) { return __builtin_bit_cast(float, __builtin_amdgcn_update_dpp(0, __builtin_bit_cast(int, v), 0x111, 0xf, 0xf, true)); }
;     __device__ __forceinline__ void operator()(const f32x4 (&acc)[2][2][4][2], const Unit& u, int wr, int wc, int fr, int fq) const {
;     ...
;                 for (int e = 0; e < 4; ++e) { pg1[e] = dpp_shr1(acc[ai][0][3][n][e]); pg2[e] = dpp_shr1(acc[ai][0][2][n][e]); pv1[e] = dpp_shr1(acc[ai][1][3][n][e]); pv2[e] = dpp_shr1(acc[ai][1][2][n][e]); }
;                 f32x4 yg[4], yv[4];
;                 yg[0] = bg + wg0 * pg2 + wg1 * pg1 + wg2 * acc[ai][0][0][n];
;                 yg[1] = bg + wg0 * pg1 + wg1 * acc[ai][0][0][n] + wg2 * acc[ai][0][1][n];
;                 yg[2] = bg + wg0 * acc[ai][0][0][n] + wg1 * acc[ai][0][1][n] + wg2 * acc[ai][0][2][n];
;                 yg[3] = bg + wg0 * acc[ai][0][1][n] + wg1 * acc[ai][0][2][n] + wg2 * acc[ai][0][3][n];
;                 yv[0] = bv + wv0 * pv2 + wv1 * pv1 + wv2 * acc[ai][1][0][n];
;                 yv[1] = bv + wv0 * pv1 + wv1 * acc[ai][1][0][n] + wv2 * acc[ai][1][1][n];
;                 yv[2] = bv + wv0 * acc[ai][1][0][n] + wv1 * acc[ai][1][1][n] + wv2 * acc[ai][1][2][n];
;                 yv[3] = bv + wv0 * acc[ai][1][1][n] + wv1 * acc[ai][1][2][n] + wv2 * acc[ai][1][3][n];
;                 bf16_t* arow = act + (size_t)(stripe * 64 + 4 * fr) * 2816 + ch0 + 4 * n;
; #pragma unroll
;                 for (int m = 0; m < 4; ++m) { f32x4 o;
; #pragma unroll
;                     for (int e = 0; e < 4; ++e) o[e] = yg[m][e] * __builtin_amdgcn_rcpf(1.0f + __expf(-yg[m][e])) * yv[m][e];
;                     *(unsigned long long*)(arow + (size_t)m * 2816) = (unsigned long long)cvt_pk_bf16(o[0], o[1]) | ((unsigned long long)cvt_pk_bf16(o[2], o[3]) << 32); }
.LBB0_1322:
	s_or_b64 exec, exec, s[6:7]
	v_mov_b32_dpp v98, v88 row_shr:1 row_mask:0xf bank_mask:0xf bound_ctrl:1
	v_mov_b32_dpp v99, v89 row_shr:1 row_mask:0xf bank_mask:0xf bound_ctrl:1
	v_mov_b32_dpp v96, v68 row_shr:1 row_mask:0xf bank_mask:0xf bound_ctrl:1
	v_mov_b32_dpp v97, v69 row_shr:1 row_mask:0xf bank_mask:0xf bound_ctrl:1
	v_pk_fma_f32 v[98:99], v[144:145], v[98:99], v[148:149]
	v_mov_b32_dpp v110, v86 row_shr:1 row_mask:0xf bank_mask:0xf bound_ctrl:1
	v_pk_fma_f32 v[98:99], v[152:153], v[96:97], v[98:99]
	v_pk_fma_f32 v[96:97], v[144:145], v[96:97], v[148:149]
	v_mov_b32_dpp v111, v87 row_shr:1 row_mask:0xf bank_mask:0xf bound_ctrl:1
	v_pk_fma_f32 v[96:97], v[92:93], v[152:153], v[96:97]
	v_mov_b32_dpp v108, v82 row_shr:1 row_mask:0xf bank_mask:0xf bound_ctrl:1
	v_pk_fma_f32 v[112:113], v[64:65], v[156:157], v[96:97]
	v_pk_fma_f32 v[96:97], v[94:95], v[146:147], v[150:151]
	v_mov_b32_dpp v109, v83 row_shr:1 row_mask:0xf bank_mask:0xf bound_ctrl:1
	v_pk_fma_f32 v[96:97], v[66:67], v[154:155], v[96:97]
	v_mov_b32_dpp v102, v84 row_shr:1 row_mask:0xf bank_mask:0xf bound_ctrl:1
	v_pk_fma_f32 v[116:117], v[90:91], v[158:159], v[96:97]
	v_pk_fma_f32 v[96:97], v[66:67], v[146:147], v[150:151]
	v_mov_b32_dpp v103, v85 row_shr:1 row_mask:0xf bank_mask:0xf bound_ctrl:1
	v_pk_fma_f32 v[96:97], v[90:91], v[154:155], v[96:97]
	v_mov_b32_dpp v100, v80 row_shr:1 row_mask:0xf bank_mask:0xf bound_ctrl:1
	v_pk_fma_f32 v[120:121], v[70:71], v[158:159], v[96:97]
	v_pk_fma_f32 v[96:97], v[130:131], v[110:111], v[134:135]
	v_mov_b32_dpp v101, v81 row_shr:1 row_mask:0xf bank_mask:0xf bound_ctrl:1
	v_pk_fma_f32 v[96:97], v[138:139], v[108:109], v[96:97]
	v_pk_fma_f32 v[98:99], v[92:93], v[156:157], v[98:99]
	v_pk_fma_f32 v[110:111], v[78:79], v[142:143], v[96:97]
	v_pk_fma_f32 v[96:97], v[130:131], v[108:109], v[134:135]
	v_pk_fma_f32 v[102:103], v[128:129], v[102:103], v[132:133]
	v_pk_fma_f32 v[96:97], v[78:79], v[138:139], v[96:97]
	v_pk_fma_f32 v[102:103], v[136:137], v[100:101], v[102:103]
	v_pk_fma_f32 v[108:109], v[74:75], v[142:143], v[96:97]
	v_pk_fma_f32 v[96:97], v[78:79], v[130:131], v[134:135]
	v_pk_fma_f32 v[100:101], v[128:129], v[100:101], v[132:133]
	v_pk_fma_f32 v[96:97], v[74:75], v[138:139], v[96:97]
	v_pk_fma_f32 v[122:123], v[76:77], v[128:129], v[132:133]
	v_pk_fma_f32 v[124:125], v[86:87], v[142:143], v[96:97]
	v_pk_fma_f32 v[96:97], v[74:75], v[130:131], v[134:135]
	v_pk_fma_f32 v[126:127], v[72:73], v[128:129], v[132:133]
	v_pk_fma_f32 v[96:97], v[86:87], v[138:139], v[96:97]
	s_add_i32 s56, s58, 2
	v_pk_fma_f32 v[128:129], v[82:83], v[142:143], v[96:97]
	v_mul_f32_e32 v96, 0xbfb8aa3b, v98
	v_exp_f32_e32 v131, v96
	v_lshl_or_b32 v130, s56, 6, v194
	v_mov_b64_e32 v[96:97], s[12:13]
	v_mad_i64_i32 v[96:97], s[6:7], v130, s81, v[96:97]
	v_add_f32_e32 v130, 1.0, v131
	v_rcp_f32_e32 v130, v130
	v_mul_f32_e32 v131, 0xbfb8aa3b, v99
	v_mov_b32_dpp v106, v90 row_shr:1 row_mask:0xf bank_mask:0xf bound_ctrl:1
	v_mov_b32_dpp v107, v91 row_shr:1 row_mask:0xf bank_mask:0xf bound_ctrl:1
	v_exp_f32_e32 v131, v131
	v_mov_b32_dpp v104, v70 row_shr:1 row_mask:0xf bank_mask:0xf bound_ctrl:1
	v_mov_b32_dpp v105, v71 row_shr:1 row_mask:0xf bank_mask:0xf bound_ctrl:1
	v_pk_fma_f32 v[106:107], v[146:147], v[106:107], v[150:151]
	v_pk_fma_f32 v[102:103], v[76:77], v[140:141], v[102:103]
	v_pk_fma_f32 v[106:107], v[154:155], v[104:105], v[106:107]
	v_mul_f32_e32 v98, v98, v130
	v_pk_fma_f32 v[106:107], v[94:95], v[158:159], v[106:107]
	v_mul_f32_e32 v98, v102, v98
	v_add_f32_e32 v102, 1.0, v131
	v_mul_f32_e32 v130, 0xbfb8aa3b, v106
	v_rcp_f32_e32 v102, v102
	v_exp_f32_e32 v130, v130
	v_mul_f32_e32 v131, 0xbfb8aa3b, v107
	v_exp_f32_e32 v131, v131
	v_mul_f32_e32 v99, v99, v102
	v_add_f32_e32 v102, 1.0, v130
	v_rcp_f32_e32 v102, v102
	v_add_f32_e32 v130, 1.0, v131
	v_rcp_f32_e32 v130, v130
	v_mul_f32_e32 v99, v103, v99
	v_mul_f32_e32 v102, v106, v102
	v_mul_f32_e32 v106, 0xbfb8aa3b, v112
	v_exp_f32_e32 v106, v106
	v_mul_f32_e32 v102, v110, v102
	v_mul_f32_e32 v103, v107, v130
	v_mul_f32_e32 v103, v111, v103
	v_cvt_pk_bf16_f32 v98, v98, v99
	v_cvt_pk_bf16_f32 v99, v102, v103
	v_add_f32_e32 v102, 1.0, v106
	v_rcp_f32_e32 v102, v102
	v_pk_fma_f32 v[104:105], v[146:147], v[104:105], v[150:151]
	v_pk_fma_f32 v[100:101], v[76:77], v[136:137], v[100:101]
	v_pk_fma_f32 v[104:105], v[94:95], v[154:155], v[104:105]
	v_lshl_add_u64 v[96:97], v[190:191], 1, v[96:97]
	v_pk_fma_f32 v[104:105], v[66:67], v[158:159], v[104:105]
	v_pk_fma_f32 v[100:101], v[72:73], v[140:141], v[100:101]
	v_mov_b32_e32 v248, v98
	v_mov_b32_e32 v249, v99
	v_mul_f32_e32 v98, v112, v102
	v_mul_f32_e32 v103, 0xbfb8aa3b, v113
	v_mul_f32_e32 v98, v100, v98
	v_mul_f32_e32 v100, 0xbfb8aa3b, v104
	v_exp_f32_e32 v103, v103
	v_exp_f32_e32 v100, v100
	v_mul_f32_e32 v102, 0xbfb8aa3b, v105
	v_exp_f32_e32 v102, v102
	v_add_f32_e32 v99, 1.0, v103
	v_add_f32_e32 v100, 1.0, v100
	v_rcp_f32_e32 v99, v99
	v_rcp_f32_e32 v100, v100
	v_add_f32_e32 v102, 1.0, v102
	v_rcp_f32_e32 v102, v102
	v_pk_fma_f32 v[114:115], v[92:93], v[144:145], v[148:149]
	v_mul_f32_e32 v99, v113, v99
	v_pk_fma_f32 v[114:115], v[64:65], v[152:153], v[114:115]
	v_mul_f32_e32 v100, v104, v100
	v_pk_fma_f32 v[114:115], v[88:89], v[156:157], v[114:115]
	v_mul_f32_e32 v99, v101, v99
	v_mul_f32_e32 v101, v108, v100
	v_mul_f32_e32 v100, v105, v102
	v_mul_f32_e32 v102, v109, v100
	v_cvt_pk_bf16_f32 v100, v98, v99
	v_mul_f32_e32 v98, 0xbfb8aa3b, v114
	v_cvt_pk_bf16_f32 v101, v101, v102
	v_exp_f32_e32 v102, v98
	v_mul_f32_e32 v103, 0xbfb8aa3b, v115
	v_exp_f32_e32 v103, v103
	v_add_co_u32_e32 v98, vcc, s82, v96
	v_add_f32_e32 v102, 1.0, v102
; __device__ __forceinline__ unsigned cvt_pk_bf16(float lo, float hi) { unsigned r; asm volatile("v_cvt_pk_bf16_f32 %0, %1, %2" : "=v"(r) : "v"(lo), "v"(hi)); return r; }
;     __device__ __forceinline__ void operator()(const f32x4 (&acc)[2][2][4][2], const Unit& u, int wr, int wc, int fr, int fq) const {
;     ...
;             const f32x4 wg0 = *(const f32x4*)(cw + ch0 + 4 * n), wg1 = *(const f32x4*)(cw + 5632 + ch0 + 4 * n), wg2 = *(const f32x4*)(cw + 2 * 5632 + ch0 + 4 * n), bg = *(const f32x4*)(cb + ch0 + 4 * n);
;             const f32x4 wv0 = *(const f32x4*)(cw + 2816 + ch0 + 4 * n), wv1 = *(const f32x4*)(cw + 5632 + 2816 + ch0 + 4 * n), wv2 = *(const f32x4*)(cw + 2 * 5632 + 2816 + ch0 + 4 * n), bv = *(const f32x4*)(cb + 2816 + ch0 + 4 * n);
;     ...
;                 for (int m = 0; m < 4; ++m) { f32x4 o;
; #pragma unroll
;                     for (int e = 0; e < 4; ++e) o[e] = yg[m][e] * __builtin_amdgcn_rcpf(1.0f + __expf(-yg[m][e])) * yv[m][e];
;                     *(unsigned long long*)(arow + (size_t)m * 2816) = (unsigned long long)cvt_pk_bf16(o[0], o[1]) | ((unsigned long long)cvt_pk_bf16(o[2], o[3]) << 32); }
;                 if (fr == 0 || fr == 15) {
;                     const int m0 = (fr == 0) ? 0 : 2;
; #pragma unroll
;                     for (int mm = 0; mm < 2; ++mm)
; #pragma unroll
;                         for (int bj = 0; bj < 2; ++bj) { const f32x4 x = (fr == 0) ? acc[ai][bj][mm][n] : acc[ai][bj][2 + mm][n];
;                             *(unsigned long long*)(edge + ((size_t)stripe * 4 + m0 + mm) * 5632 + ucol + bj * HALF + 4 * n) = (unsigned long long)cvt_pk_bf16(x[0], x[1]) | ((unsigned long long)cvt_pk_bf16(x[2], x[3]) << 32); }
	v_rcp_f32_e32 v102, v102
	v_addc_co_u32_e32 v99, vcc, 0, v97, vcc
	v_mov_b32_e32 v250, v100
	v_mov_b32_e32 v251, v101
	v_mul_f32_e32 v100, v114, v102
	v_mul_f32_e32 v102, 0xbfb8aa3b, v116
	v_add_f32_e32 v101, 1.0, v103
	v_exp_f32_e32 v102, v102
	v_mul_f32_e32 v103, 0xbfb8aa3b, v117
	v_exp_f32_e32 v103, v103
	v_rcp_f32_e32 v101, v101
	v_add_f32_e32 v102, 1.0, v102
	v_rcp_f32_e32 v102, v102
	v_add_f32_e32 v103, 1.0, v103
	v_rcp_f32_e32 v103, v103
	v_pk_fma_f32 v[118:119], v[64:65], v[144:145], v[148:149]
	v_pk_fma_f32 v[122:123], v[72:73], v[136:137], v[122:123]
	v_pk_fma_f32 v[118:119], v[88:89], v[152:153], v[118:119]
	v_pk_fma_f32 v[122:123], v[84:85], v[140:141], v[122:123]
	v_mul_f32_e32 v102, v116, v102
	v_pk_fma_f32 v[118:119], v[68:69], v[156:157], v[118:119]
	v_mul_f32_e32 v100, v122, v100
	v_mul_f32_e32 v101, v115, v101
	v_mul_f32_e32 v104, v124, v102
	v_mul_f32_e32 v102, v117, v103
	v_mul_f32_e32 v101, v123, v101
	v_mul_f32_e32 v103, v125, v102
	v_cvt_pk_bf16_f32 v102, v100, v101
	v_mul_f32_e32 v100, 0xbfb8aa3b, v118
	v_cvt_pk_bf16_f32 v103, v104, v103
	v_exp_f32_e32 v104, v100
	v_mul_f32_e32 v105, 0xbfb8aa3b, v119
	v_exp_f32_e32 v105, v105
	v_add_co_u32_e32 v100, vcc, s72, v96
	v_add_f32_e32 v104, 1.0, v104
	v_rcp_f32_e32 v104, v104
	v_addc_co_u32_e32 v101, vcc, 0, v97, vcc
	v_mov_b32_e32 v252, v102
	v_mov_b32_e32 v253, v103
	v_mul_f32_e32 v102, v118, v104
	v_mul_f32_e32 v104, 0xbfb8aa3b, v120
	v_add_f32_e32 v103, 1.0, v105
	v_exp_f32_e32 v104, v104
	v_mul_f32_e32 v105, 0xbfb8aa3b, v121
	v_exp_f32_e32 v105, v105
	v_rcp_f32_e32 v103, v103
	v_add_f32_e32 v104, 1.0, v104
	v_rcp_f32_e32 v104, v104
	v_add_f32_e32 v105, 1.0, v105
	v_rcp_f32_e32 v105, v105
	v_pk_fma_f32 v[126:127], v[84:85], v[136:137], v[126:127]
	v_mul_f32_e32 v103, v119, v103
	v_pk_fma_f32 v[126:127], v[80:81], v[140:141], v[126:127]
	v_mul_f32_e32 v104, v120, v104
	v_mul_f32_e32 v102, v126, v102
	v_mul_f32_e32 v103, v127, v103
	v_mul_f32_e32 v104, v128, v104
	v_mul_f32_e32 v105, v121, v105
	v_mul_f32_e32 v105, v129, v105
	v_cvt_pk_bf16_f32 v102, v102, v103
	v_cvt_pk_bf16_f32 v103, v104, v105
	v_add_co_u32_e32 v104, vcc, 0x4000, v96
	s_mov_b64 s[8:9], -1
	s_nop 0
	v_addc_co_u32_e32 v105, vcc, 0, v97, vcc
	v_cmp_gt_i32_e32 vcc, 15, v169
	v_mov_b32_e32 v234, v102
	v_mov_b32_e32 v235, v103
	s_and_saveexec_b64 s[6:7], vcc
	v_cmp_eq_u32_e32 vcc, 0, v169
	s_orn2_b64 s[8:9], vcc, exec
	s_or_b64 exec, exec, s[6:7]
	s_and_saveexec_b64 s[6:7], s[8:9]
	s_cbranch_execz .LBB0_1326
	s_ashr_i32 s57, s56, 31
	s_lshl_b64 s[8:9], s[56:57], 2
	v_cndmask_b32_e64 v90, v90, v94, s[0:1]
	v_cndmask_b32_e64 v91, v91, v95, s[0:1]
	v_cndmask_b32_e64 v88, v88, v92, s[0:1]
	v_cndmask_b32_e64 v89, v89, v93, s[0:1]
	v_or_b32_e32 v102, s8, v168
	v_cvt_pk_bf16_f32 v88, v88, v89
	v_cvt_pk_bf16_f32 v89, v90, v91
	v_mov_b64_e32 v[90:91], s[14:15]
	v_mad_u64_u32 v[90:91], s[28:29], v102, s83, v[90:91]
	v_mad_i32_i24 v91, s9, v198, v91
	v_lshl_add_u64 v[90:91], v[178:179], 1, v[90:91]
	v_cndmask_b32_e64 v76, v84, v76, s[0:1]
	v_cndmask_b32_e64 v77, v85, v77, s[0:1]
	v_cndmask_b32_e64 v64, v68, v64, s[0:1]
	v_cndmask_b32_e64 v65, v69, v65, s[0:1]
	v_add_co_u32_e32 v68, vcc, s72, v90
	global_store_dwordx2 v[90:91], v[88:89], off
	v_cndmask_b32_e64 v78, v86, v78, s[0:1]
	v_cndmask_b32_e64 v79, v87, v79, s[0:1]
	v_cvt_pk_bf16_f32 v76, v76, v77
	v_cvt_pk_bf16_f32 v77, v78, v79
	global_store_dwordx2 v[90:91], v[76:77], off offset:256
	v_cndmask_b32_e64 v66, v70, v66, s[0:1]
	v_cndmask_b32_e64 v67, v71, v67, s[0:1]
	v_cvt_pk_bf16_f32 v64, v64, v65
	v_cvt_pk_bf16_f32 v65, v66, v67
	v_addc_co_u32_e32 v69, vcc, 0, v91, vcc
	v_lshl_add_u64 v[66:67], v[90:91], 0, s[24:25]
	global_store_dwordx2 v[68:69], v[64:65], off offset:3072
	v_cndmask_b32_e64 v65, v82, v74, s[0:1]
	v_cndmask_b32_e64 v64, v80, v72, s[0:1]
	v_cndmask_b32_e64 v68, v83, v75, s[0:1]
	v_cndmask_b32_e64 v69, v81, v73, s[0:1]
	v_cvt_pk_bf16_f32 v64, v64, v69
	v_cvt_pk_bf16_f32 v65, v65, v68
	global_store_dwordx2 v[66:67], v[64:65], off offset:256
.LBB0_1326:
	s_or_b64 exec, exec, s[6:7]
	v_add_co_u32_e32 v64, vcc, 0x5000, v182
	global_load_dwordx4 v[76:79], v[182:183], off offset:16
	s_nop 0
	v_addc_co_u32_e32 v65, vcc, 0, v183, vcc
	global_load_dwordx4 v[88:91], v[184:185], off offset:16
	v_add_co_u32_e32 v66, vcc, 0xb000, v182
	v_mov_b32_dpp v104, v56 row_shr:1 row_mask:0xf bank_mask:0xf bound_ctrl:1
	s_nop 0
	v_addc_co_u32_e32 v67, vcc, 0, v183, vcc
	global_load_dwordx4 v[92:95], v[64:65], off offset:2064
	global_load_dwordx4 v[84:87], v[66:67], off offset:16
	v_add_co_u32_e32 v64, vcc, s72, v182
	v_mov_b32_dpp v105, v57 row_shr:1 row_mask:0xf bank_mask:0xf bound_ctrl:1
	s_nop 0
	v_addc_co_u32_e32 v65, vcc, 0, v183, vcc
	v_add_co_u32_e32 v68, vcc, s76, v182
	s_mov_b64 s[6:7], vcc
	v_add_co_u32_e32 v70, vcc, 0xd000, v182
	s_mov_b64 s[8:9], vcc
	v_add_co_u32_e32 v72, vcc, s72, v184
	global_load_dwordx4 v[64:67], v[64:65], off offset:3088
	s_nop 0
	v_addc_co_u32_e32 v73, vcc, 0, v185, vcc
	global_load_dwordx4 v[80:83], v[72:73], off offset:3088
	v_addc_co_u32_e64 v69, vcc, 0, v183, s[6:7]
	global_load_dwordx4 v[72:75], v[68:69], off offset:1040
	v_addc_co_u32_e64 v71, vcc, 0, v183, s[8:9]
	global_load_dwordx4 v[68:71], v[70:71], off offset:3088
	v_mov_b32_dpp v102, v44 row_shr:1 row_mask:0xf bank_mask:0xf bound_ctrl:1
	v_mov_b32_dpp v103, v45 row_shr:1 row_mask:0xf bank_mask:0xf bound_ctrl:1
	v_mov_b32_dpp v108, v40 row_shr:1 row_mask:0xf bank_mask:0xf bound_ctrl:1
	v_mov_b32_dpp v109, v41 row_shr:1 row_mask:0xf bank_mask:0xf bound_ctrl:1
	v_mov_b32_dpp v112, v58 row_shr:1 row_mask:0xf bank_mask:0xf bound_ctrl:1
	v_mov_b32_dpp v113, v59 row_shr:1 row_mask:0xf bank_mask:0xf bound_ctrl:1
	v_mov_b32_dpp v106, v32 row_shr:1 row_mask:0xf bank_mask:0xf bound_ctrl:1
	v_mov_b32_dpp v107, v33 row_shr:1 row_mask:0xf bank_mask:0xf bound_ctrl:1
	v_mov_b32_dpp v110, v46 row_shr:1 row_mask:0xf bank_mask:0xf bound_ctrl:1
	v_mov_b32_dpp v111, v47 row_shr:1 row_mask:0xf bank_mask:0xf bound_ctrl:1
	v_mov_b32_dpp v116, v42 row_shr:1 row_mask:0xf bank_mask:0xf bound_ctrl:1
	v_mov_b32_dpp v117, v43 row_shr:1 row_mask:0xf bank_mask:0xf bound_ctrl:1
	v_mov_b32_dpp v114, v34 row_shr:1 row_mask:0xf bank_mask:0xf bound_ctrl:1
	v_mov_b32_dpp v115, v35 row_shr:1 row_mask:0xf bank_mask:0xf bound_ctrl:1
	s_mov_b64 s[8:9], -1
	s_waitcnt vmcnt(6)
; __device__ __forceinline__ unsigned cvt_pk_bf16(float lo, float hi) { unsigned r; asm volatile("v_cvt_pk_bf16_f32 %0, %1, %2" : "=v"(r) : "v"(lo), "v"(hi)); return r; }
; __device__ __forceinline__ float dpp_shr1(float v) { return __builtin_bit_cast(float, __builtin_amdgcn_update_dpp(0, __builtin_bit_cast(int, v), 0x111, 0xf, 0xf, true)); }
;     __device__ __forceinline__ void operator()(const f32x4 (&acc)[2][2][4][2], const Unit& u, int wr, int wc, int fr, int fq) const {
;     ...
;                 for (int e = 0; e < 4; ++e) { pg1[e] = dpp_shr1(acc[ai][0][3][n][e]); pg2[e] = dpp_shr1(acc[ai][0][2][n][e]); pv1[e] = dpp_shr1(acc[ai][1][3][n][e]); pv2[e] = dpp_shr1(acc[ai][1][2][n][e]); }
;                 f32x4 yg[4], yv[4];
;                 yg[0] = bg + wg0 * pg2 + wg1 * pg1 + wg2 * acc[ai][0][0][n];
;                 yg[1] = bg + wg0 * pg1 + wg1 * acc[ai][0][0][n] + wg2 * acc[ai][0][1][n];
;                 yg[2] = bg + wg0 * acc[ai][0][0][n] + wg1 * acc[ai][0][1][n] + wg2 * acc[ai][0][2][n];
;                 yg[3] = bg + wg0 * acc[ai][0][1][n] + wg1 * acc[ai][0][2][n] + wg2 * acc[ai][0][3][n];
;                 yv[0] = bv + wv0 * pv2 + wv1 * pv1 + wv2 * acc[ai][1][0][n];
;                 yv[1] = bv + wv0 * pv1 + wv1 * acc[ai][1][0][n] + wv2 * acc[ai][1][1][n];
;                 yv[2] = bv + wv0 * acc[ai][1][0][n] + wv1 * acc[ai][1][1][n] + wv2 * acc[ai][1][2][n];
;                 yv[3] = bv + wv0 * acc[ai][1][1][n] + wv1 * acc[ai][1][2][n] + wv2 * acc[ai][1][3][n];
;                 bf16_t* arow = act + (size_t)(stripe * 64 + 4 * fr) * 2816 + ch0 + 4 * n;
; #pragma unroll
;                 for (int m = 0; m < 4; ++m) { f32x4 o;
; #pragma unroll
;                     for (int e = 0; e < 4; ++e) o[e] = yg[m][e] * __builtin_amdgcn_rcpf(1.0f + __expf(-yg[m][e])) * yv[m][e];
;                     *(unsigned long long*)(arow + (size_t)m * 2816) = (unsigned long long)cvt_pk_bf16(o[0], o[1]) | ((unsigned long long)cvt_pk_bf16(o[2], o[3]) << 32); }
	v_pk_fma_f32 v[104:105], v[76:77], v[104:105], v[88:89]
	v_pk_fma_f32 v[120:121], v[76:77], v[102:103], v[88:89]
	v_pk_fma_f32 v[112:113], v[78:79], v[112:113], v[90:91]
	v_pk_fma_f32 v[124:125], v[60:61], v[76:77], v[88:89]
	v_pk_fma_f32 v[128:129], v[52:53], v[76:77], v[88:89]
	s_waitcnt vmcnt(5)
	v_pk_fma_f32 v[102:103], v[92:93], v[102:103], v[104:105]
	v_pk_fma_f32 v[118:119], v[78:79], v[110:111], v[90:91]
	s_waitcnt vmcnt(4)
	v_pk_fma_f32 v[102:103], v[60:61], v[84:85], v[102:103]
	v_pk_fma_f32 v[104:105], v[94:95], v[110:111], v[112:113]
	v_mul_f32_e32 v134, 0xbfb8aa3b, v102
	v_exp_f32_e32 v134, v134
	v_mul_f32_e32 v135, 0xbfb8aa3b, v103
	v_exp_f32_e32 v135, v135
	v_pk_fma_f32 v[110:111], v[60:61], v[92:93], v[120:121]
	v_add_f32_e32 v134, 1.0, v134
	v_rcp_f32_e32 v134, v134
	v_pk_fma_f32 v[120:121], v[52:53], v[92:93], v[124:125]
	v_pk_fma_f32 v[124:125], v[56:57], v[92:93], v[128:129]
	v_pk_fma_f32 v[104:105], v[62:63], v[86:87], v[104:105]
	v_mul_f32_e32 v102, v102, v134
	v_mul_f32_e32 v134, 0xbfb8aa3b, v104
	v_exp_f32_e32 v134, v134
	v_pk_fma_f32 v[110:111], v[52:53], v[84:85], v[110:111]
	s_waitcnt vmcnt(2)
	v_pk_fma_f32 v[108:109], v[64:65], v[108:109], v[80:81]
	v_pk_fma_f32 v[128:129], v[64:65], v[106:107], v[80:81]
	v_pk_fma_f32 v[116:117], v[66:67], v[116:117], v[82:83]
	s_waitcnt vmcnt(1)
	v_pk_fma_f32 v[106:107], v[72:73], v[106:107], v[108:109]
	v_pk_fma_f32 v[108:109], v[74:75], v[114:115], v[116:117]
	v_pk_fma_f32 v[112:113], v[62:63], v[94:95], v[118:119]
	s_waitcnt vmcnt(0)
	v_pk_fma_f32 v[106:107], v[48:49], v[68:69], v[106:107]
	v_pk_fma_f32 v[108:109], v[50:51], v[70:71], v[108:109]
	v_mul_f32_e32 v102, v106, v102
	v_add_f32_e32 v106, 1.0, v135
	v_rcp_f32_e32 v106, v106
	v_mul_f32_e32 v135, 0xbfb8aa3b, v105
	v_exp_f32_e32 v135, v135
	v_pk_fma_f32 v[112:113], v[54:55], v[86:87], v[112:113]
	v_mul_f32_e32 v103, v103, v106
	v_add_f32_e32 v106, 1.0, v134
	v_rcp_f32_e32 v106, v106
	v_add_f32_e32 v134, 1.0, v135
	v_rcp_f32_e32 v134, v134
	v_mul_f32_e32 v103, v107, v103
	v_mul_f32_e32 v104, v104, v106
	v_mul_f32_e32 v106, 0xbfb8aa3b, v110
	v_exp_f32_e32 v106, v106
	v_mul_f32_e32 v104, v108, v104
	v_mul_f32_e32 v105, v105, v134
	v_mul_f32_e32 v105, v109, v105
	v_cvt_pk_bf16_f32 v102, v102, v103
	v_cvt_pk_bf16_f32 v103, v104, v105
	v_add_f32_e32 v104, 1.0, v106
	v_rcp_f32_e32 v104, v104
	v_mul_f32_e32 v105, 0xbfb8aa3b, v111
	v_exp_f32_e32 v105, v105
	v_mov_b32_e32 v236, v240
	v_mov_b32_e32 v237, v241
	v_mov_b32_e32 v238, v102
	v_mov_b32_e32 v239, v103
	global_store_dwordx4 v[180:181], v[236:239], off
	v_mul_f32_e32 v102, v110, v104
	v_mul_f32_e32 v104, 0xbfb8aa3b, v112
	v_add_f32_e32 v103, 1.0, v105
	v_exp_f32_e32 v104, v104
	v_mul_f32_e32 v105, 0xbfb8aa3b, v113
	v_exp_f32_e32 v105, v105
	v_pk_fma_f32 v[120:121], v[56:57], v[84:85], v[120:121]
	v_add_f32_e32 v104, 1.0, v104
	v_rcp_f32_e32 v103, v103
	v_rcp_f32_e32 v104, v104
	v_add_f32_e32 v105, 1.0, v105
	v_pk_fma_f32 v[122:123], v[62:63], v[78:79], v[90:91]
	v_pk_fma_f32 v[126:127], v[54:55], v[78:79], v[90:91]
	v_rcp_f32_e32 v105, v105
	v_mul_f32_e32 v106, 0xbfb8aa3b, v120
	v_pk_fma_f32 v[118:119], v[54:55], v[94:95], v[122:123]
	v_pk_fma_f32 v[122:123], v[58:59], v[94:95], v[126:127]
	v_pk_fma_f32 v[126:127], v[66:67], v[114:115], v[82:83]
	v_exp_f32_e32 v106, v106
	v_pk_fma_f32 v[114:115], v[48:49], v[72:73], v[128:129]
	v_pk_fma_f32 v[116:117], v[50:51], v[74:75], v[126:127]
	v_pk_fma_f32 v[114:115], v[36:37], v[68:69], v[114:115]
	v_pk_fma_f32 v[116:117], v[38:39], v[70:71], v[116:117]
	v_mul_f32_e32 v103, v111, v103
	v_mul_f32_e32 v104, v112, v104
	v_mul_f32_e32 v102, v114, v102
	v_mul_f32_e32 v103, v115, v103
	v_mul_f32_e32 v104, v116, v104
	v_mul_f32_e32 v105, v113, v105
	v_mul_f32_e32 v105, v117, v105
	v_cvt_pk_bf16_f32 v102, v102, v103
	v_cvt_pk_bf16_f32 v103, v104, v105
	v_add_f32_e32 v104, 1.0, v106
	v_rcp_f32_e32 v104, v104
	v_mul_f32_e32 v105, 0xbfb8aa3b, v121
	v_exp_f32_e32 v105, v105
	v_pk_fma_f32 v[118:119], v[58:59], v[86:87], v[118:119]
	v_mov_b32_e32 v236, v242
	v_mov_b32_e32 v237, v243
	v_mov_b32_e32 v238, v102
	v_mov_b32_e32 v239, v103
	global_store_dwordx4 v[186:187], v[236:239], off offset:1536
	v_mul_f32_e32 v102, v120, v104
	v_mul_f32_e32 v104, 0xbfb8aa3b, v118
	v_add_f32_e32 v103, 1.0, v105
	v_exp_f32_e32 v104, v104
	v_mul_f32_e32 v105, 0xbfb8aa3b, v119
	v_exp_f32_e32 v105, v105
	v_pk_fma_f32 v[124:125], v[44:45], v[84:85], v[124:125]
	v_add_f32_e32 v104, 1.0, v104
	v_rcp_f32_e32 v103, v103
	v_rcp_f32_e32 v104, v104
	v_add_f32_e32 v105, 1.0, v105
	v_rcp_f32_e32 v105, v105
	v_mul_f32_e32 v106, 0xbfb8aa3b, v124
	v_pk_fma_f32 v[126:127], v[50:51], v[66:67], v[82:83]
	v_pk_fma_f32 v[128:129], v[48:49], v[64:65], v[80:81]
	v_exp_f32_e32 v106, v106
	v_pk_fma_f32 v[126:127], v[38:39], v[74:75], v[126:127]
	v_pk_fma_f32 v[128:129], v[36:37], v[72:73], v[128:129]
	v_pk_fma_f32 v[126:127], v[42:43], v[70:71], v[126:127]
	v_pk_fma_f32 v[128:129], v[40:41], v[68:69], v[128:129]
	v_mul_f32_e32 v103, v121, v103
	v_mul_f32_e32 v104, v118, v104
	v_mul_f32_e32 v102, v128, v102
	v_mul_f32_e32 v103, v129, v103
	v_mul_f32_e32 v104, v126, v104
	v_mul_f32_e32 v105, v119, v105
	v_mul_f32_e32 v105, v127, v105
	v_cvt_pk_bf16_f32 v102, v102, v103
	v_cvt_pk_bf16_f32 v103, v104, v105
	v_add_f32_e32 v104, 1.0, v106
	v_rcp_f32_e32 v104, v104
	v_mul_f32_e32 v105, 0xbfb8aa3b, v125
	v_exp_f32_e32 v105, v105
	v_pk_fma_f32 v[122:123], v[46:47], v[86:87], v[122:123]
	v_mov_b32_e32 v236, v244
	v_mov_b32_e32 v237, v245
	v_mov_b32_e32 v238, v102
	v_mov_b32_e32 v239, v103
	global_store_dwordx4 v[188:189], v[236:239], off offset:3072
	v_mul_f32_e32 v102, v124, v104
	v_mul_f32_e32 v104, 0xbfb8aa3b, v122
	v_add_f32_e32 v103, 1.0, v105
	v_exp_f32_e32 v104, v104
	v_mul_f32_e32 v105, 0xbfb8aa3b, v123
	v_exp_f32_e32 v105, v105
	v_rcp_f32_e32 v103, v103
	v_add_f32_e32 v104, 1.0, v104
	v_rcp_f32_e32 v104, v104
	v_add_f32_e32 v105, 1.0, v105
	v_rcp_f32_e32 v105, v105
	v_pk_fma_f32 v[130:131], v[38:39], v[66:67], v[82:83]
	v_pk_fma_f32 v[132:133], v[36:37], v[64:65], v[80:81]
	v_pk_fma_f32 v[130:131], v[42:43], v[74:75], v[130:131]
	v_pk_fma_f32 v[132:133], v[40:41], v[72:73], v[132:133]
	v_pk_fma_f32 v[130:131], v[34:35], v[70:71], v[130:131]
	v_pk_fma_f32 v[132:133], v[32:33], v[68:69], v[132:133]
	v_mul_f32_e32 v103, v125, v103
	v_mul_f32_e32 v104, v122, v104
	v_mul_f32_e32 v102, v132, v102
	v_mul_f32_e32 v103, v133, v103
	v_mul_f32_e32 v104, v130, v104
	v_mul_f32_e32 v105, v123, v105
	v_mul_f32_e32 v105, v131, v105
	v_cvt_pk_bf16_f32 v102, v102, v103
	v_cvt_pk_bf16_f32 v103, v104, v105
	v_add_co_u32_e32 v104, vcc, 0x4000, v180
	s_nop 1
	v_addc_co_u32_e32 v105, vcc, 0, v181, vcc
	v_cmp_gt_i32_e32 vcc, 15, v169
	v_mov_b32_e32 v236, v246
	v_mov_b32_e32 v237, v247
	v_mov_b32_e32 v238, v102
	v_mov_b32_e32 v239, v103
	global_store_dwordx4 v[104:105], v[236:239], off offset:512
	s_and_saveexec_b64 s[6:7], vcc
	v_cmp_eq_u32_e32 vcc, 0, v169
	s_orn2_b64 s[8:9], vcc, exec
	s_or_b64 exec, exec, s[6:7]
	s_and_saveexec_b64 s[6:7], s[8:9]
	s_cbranch_execz .LBB0_1330
; __device__ __forceinline__ unsigned cvt_pk_bf16(float lo, float hi) { unsigned r; asm volatile("v_cvt_pk_bf16_f32 %0, %1, %2" : "=v"(r) : "v"(lo), "v"(hi)); return r; }
; __device__ __forceinline__ float dpp_shr1(float v) { return __builtin_bit_cast(float, __builtin_amdgcn_update_dpp(0, __builtin_bit_cast(int, v), 0x111, 0xf, 0xf, true)); }
;     __device__ __forceinline__ void operator()(const f32x4 (&acc)[2][2][4][2], const Unit& u, int wr, int wc, int fr, int fq) const {
;     ...
;                 for (int e = 0; e < 4; ++e) { pg1[e] = dpp_shr1(acc[ai][0][3][n][e]); pg2[e] = dpp_shr1(acc[ai][0][2][n][e]); pv1[e] = dpp_shr1(acc[ai][1][3][n][e]); pv2[e] = dpp_shr1(acc[ai][1][2][n][e]); }
;                 f32x4 yg[4], yv[4];
;                 yg[0] = bg + wg0 * pg2 + wg1 * pg1 + wg2 * acc[ai][0][0][n];
;                 yg[1] = bg + wg0 * pg1 + wg1 * acc[ai][0][0][n] + wg2 * acc[ai][0][1][n];
;                 yg[2] = bg + wg0 * acc[ai][0][0][n] + wg1 * acc[ai][0][1][n] + wg2 * acc[ai][0][2][n];
;                 yg[3] = bg + wg0 * acc[ai][0][1][n] + wg1 * acc[ai][0][2][n] + wg2 * acc[ai][0][3][n];
;                 yv[0] = bv + wv0 * pv2 + wv1 * pv1 + wv2 * acc[ai][1][0][n];
;                 yv[1] = bv + wv0 * pv1 + wv1 * acc[ai][1][0][n] + wv2 * acc[ai][1][1][n];
;                 yv[2] = bv + wv0 * acc[ai][1][0][n] + wv1 * acc[ai][1][1][n] + wv2 * acc[ai][1][2][n];
;                 yv[3] = bv + wv0 * acc[ai][1][1][n] + wv1 * acc[ai][1][2][n] + wv2 * acc[ai][1][3][n];
;     ...
;                 if (fr == 0 || fr == 15) {
;                     const int m0 = (fr == 0) ? 0 : 2;
; #pragma unroll
;                     for (int mm = 0; mm < 2; ++mm)
; #pragma unroll
;                         for (int bj = 0; bj < 2; ++bj) { const f32x4 x = (fr == 0) ? acc[ai][bj][mm][n] : acc[ai][bj][2 + mm][n];
;                             *(unsigned long long*)(edge + ((size_t)stripe * 4 + m0 + mm) * 5632 + ucol + bj * HALF + 4 * n) = (unsigned long long)cvt_pk_bf16(x[0], x[1]) | ((unsigned long long)cvt_pk_bf16(x[2], x[3]) << 32); }
	s_ashr_i32 s59, s58, 31
	s_lshl_b64 s[8:9], s[58:59], 2
	v_cndmask_b32_e64 v58, v58, v62, s[0:1]
	v_cndmask_b32_e64 v59, v59, v63, s[0:1]
	v_cndmask_b32_e64 v56, v56, v60, s[0:1]
	v_cndmask_b32_e64 v57, v57, v61, s[0:1]
	v_or_b32_e32 v102, s8, v168
	v_cvt_pk_bf16_f32 v56, v56, v57
	v_cvt_pk_bf16_f32 v57, v58, v59
	v_mov_b64_e32 v[58:59], s[14:15]
	v_mad_u64_u32 v[58:59], s[28:29], v102, s83, v[58:59]
	v_mad_i32_i24 v59, s9, v198, v59
	v_lshl_add_u64 v[58:59], v[178:179], 1, v[58:59]
	v_cndmask_b32_e64 v40, v40, v48, s[0:1]
	v_cndmask_b32_e64 v41, v41, v49, s[0:1]
	global_store_dwordx2 v[58:59], v[56:57], off offset:8
	v_cndmask_b32_e64 v42, v42, v50, s[0:1]
	v_cndmask_b32_e64 v43, v43, v51, s[0:1]
	v_cvt_pk_bf16_f32 v40, v40, v41
	v_cvt_pk_bf16_f32 v41, v42, v43
	global_store_dwordx2 v[58:59], v[40:41], off offset:264
	v_cndmask_b32_e64 v41, v46, v54, s[0:1]
	v_cndmask_b32_e64 v42, v47, v55, s[0:1]
	v_cndmask_b32_e64 v40, v44, v52, s[0:1]
	v_cndmask_b32_e64 v43, v45, v53, s[0:1]
	v_cvt_pk_bf16_f32 v40, v40, v43
	v_cvt_pk_bf16_f32 v41, v41, v42
	v_lshl_add_u64 v[42:43], v[58:59], 0, s[24:25]
	v_cndmask_b32_e64 v32, v32, v36, s[0:1]
	v_cndmask_b32_e64 v33, v33, v37, s[0:1]
	global_store_dwordx2 v[42:43], v[40:41], off offset:8
	v_cndmask_b32_e64 v34, v34, v38, s[0:1]
	v_cndmask_b32_e64 v35, v35, v39, s[0:1]
	v_cvt_pk_bf16_f32 v32, v32, v33
	v_cvt_pk_bf16_f32 v33, v34, v35
	global_store_dwordx2 v[42:43], v[32:33], off offset:264
.LBB0_1330:
	s_or_b64 exec, exec, s[6:7]
	v_mov_b32_dpp v34, v16 row_shr:1 row_mask:0xf bank_mask:0xf bound_ctrl:1
	v_mov_b32_dpp v35, v17 row_shr:1 row_mask:0xf bank_mask:0xf bound_ctrl:1
	v_mov_b32_dpp v32, v8 row_shr:1 row_mask:0xf bank_mask:0xf bound_ctrl:1
	v_mov_b32_dpp v33, v9 row_shr:1 row_mask:0xf bank_mask:0xf bound_ctrl:1
	v_pk_fma_f32 v[34:35], v[76:77], v[34:35], v[88:89]
	v_mov_b32_dpp v38, v28 row_shr:1 row_mask:0xf bank_mask:0xf bound_ctrl:1
	v_mov_b32_dpp v39, v29 row_shr:1 row_mask:0xf bank_mask:0xf bound_ctrl:1
	v_pk_fma_f32 v[34:35], v[92:93], v[32:33], v[34:35]
	v_mov_b32_dpp v36, v24 row_shr:1 row_mask:0xf bank_mask:0xf bound_ctrl:1
	v_mov_b32_dpp v37, v25 row_shr:1 row_mask:0xf bank_mask:0xf bound_ctrl:1
	v_pk_fma_f32 v[34:35], v[4:5], v[84:85], v[34:35]
	v_pk_fma_f32 v[38:39], v[64:65], v[38:39], v[80:81]
	v_pk_fma_f32 v[58:59], v[20:21], v[64:65], v[80:81]
	v_pk_fma_f32 v[38:39], v[72:73], v[36:37], v[38:39]
	v_pk_fma_f32 v[36:37], v[64:65], v[36:37], v[80:81]
	v_pk_fma_f32 v[62:63], v[12:13], v[64:65], v[80:81]
	v_mul_f32_e32 v64, 0xbfb8aa3b, v34
	v_exp_f32_e32 v64, v64
	v_mul_f32_e32 v65, 0xbfb8aa3b, v35
	v_mov_b32_dpp v42, v18 row_shr:1 row_mask:0xf bank_mask:0xf bound_ctrl:1
	v_mov_b32_dpp v43, v19 row_shr:1 row_mask:0xf bank_mask:0xf bound_ctrl:1
	v_add_f32_e32 v64, 1.0, v64
	v_rcp_f32_e32 v64, v64
	v_exp_f32_e32 v65, v65
	v_mov_b32_dpp v40, v10 row_shr:1 row_mask:0xf bank_mask:0xf bound_ctrl:1
	v_mov_b32_dpp v41, v11 row_shr:1 row_mask:0xf bank_mask:0xf bound_ctrl:1
	v_pk_fma_f32 v[42:43], v[78:79], v[42:43], v[90:91]
	v_pk_fma_f32 v[38:39], v[20:21], v[68:69], v[38:39]
	v_pk_fma_f32 v[42:43], v[94:95], v[40:41], v[42:43]
	v_mul_f32_e32 v34, v34, v64
	v_pk_fma_f32 v[42:43], v[6:7], v[86:87], v[42:43]
	v_mul_f32_e32 v34, v38, v34
	v_add_f32_e32 v38, 1.0, v65
	v_mul_f32_e32 v64, 0xbfb8aa3b, v42
	v_rcp_f32_e32 v38, v38
	v_exp_f32_e32 v64, v64
	v_mul_f32_e32 v65, 0xbfb8aa3b, v43
	v_exp_f32_e32 v65, v65
	v_mul_f32_e32 v35, v35, v38
	v_add_f32_e32 v38, 1.0, v64
	v_rcp_f32_e32 v38, v38
	v_pk_fma_f32 v[32:33], v[76:77], v[32:33], v[88:89]
	v_add_f32_e32 v64, 1.0, v65
	v_pk_fma_f32 v[32:33], v[4:5], v[92:93], v[32:33]
	v_rcp_f32_e32 v64, v64
	v_pk_fma_f32 v[32:33], v[0:1], v[84:85], v[32:33]
	v_mov_b32_dpp v46, v30 row_shr:1 row_mask:0xf bank_mask:0xf bound_ctrl:1
	v_mov_b32_dpp v47, v31 row_shr:1 row_mask:0xf bank_mask:0xf bound_ctrl:1
	v_mul_f32_e32 v38, v42, v38
	v_mul_f32_e32 v42, 0xbfb8aa3b, v32
	v_mov_b32_dpp v44, v26 row_shr:1 row_mask:0xf bank_mask:0xf bound_ctrl:1
	v_mov_b32_dpp v45, v27 row_shr:1 row_mask:0xf bank_mask:0xf bound_ctrl:1
	v_pk_fma_f32 v[46:47], v[66:67], v[46:47], v[82:83]
	v_exp_f32_e32 v42, v42
	v_pk_fma_f32 v[46:47], v[74:75], v[44:45], v[46:47]
	v_mul_f32_e32 v35, v39, v35
	v_pk_fma_f32 v[46:47], v[22:23], v[70:71], v[46:47]
	v_mul_f32_e32 v39, v43, v64
	v_mul_f32_e32 v38, v46, v38
	v_mul_f32_e32 v39, v47, v39
	v_cvt_pk_bf16_f32 v34, v34, v35
	v_cvt_pk_bf16_f32 v35, v38, v39
	v_add_f32_e32 v38, 1.0, v42
	v_mul_f32_e32 v39, 0xbfb8aa3b, v33
	v_rcp_f32_e32 v38, v38
	v_exp_f32_e32 v39, v39
	v_pk_fma_f32 v[40:41], v[78:79], v[40:41], v[90:91]
; __device__ __forceinline__ unsigned cvt_pk_bf16(float lo, float hi) { unsigned r; asm volatile("v_cvt_pk_bf16_f32 %0, %1, %2" : "=v"(r) : "v"(lo), "v"(hi)); return r; }
;     __device__ __forceinline__ void operator()(const f32x4 (&acc)[2][2][4][2], const Unit& u, int wr, int wc, int fr, int fq) const {
;     ...
;                 yg[0] = bg + wg0 * pg2 + wg1 * pg1 + wg2 * acc[ai][0][0][n];
;                 yg[1] = bg + wg0 * pg1 + wg1 * acc[ai][0][0][n] + wg2 * acc[ai][0][1][n];
;                 yg[2] = bg + wg0 * acc[ai][0][0][n] + wg1 * acc[ai][0][1][n] + wg2 * acc[ai][0][2][n];
;                 yg[3] = bg + wg0 * acc[ai][0][1][n] + wg1 * acc[ai][0][2][n] + wg2 * acc[ai][0][3][n];
;                 yv[0] = bv + wv0 * pv2 + wv1 * pv1 + wv2 * acc[ai][1][0][n];
;                 yv[1] = bv + wv0 * pv1 + wv1 * acc[ai][1][0][n] + wv2 * acc[ai][1][1][n];
;                 yv[2] = bv + wv0 * acc[ai][1][0][n] + wv1 * acc[ai][1][1][n] + wv2 * acc[ai][1][2][n];
;                 yv[3] = bv + wv0 * acc[ai][1][1][n] + wv1 * acc[ai][1][2][n] + wv2 * acc[ai][1][3][n];
;                 bf16_t* arow = act + (size_t)(stripe * 64 + 4 * fr) * 2816 + ch0 + 4 * n;
; #pragma unroll
;                 for (int m = 0; m < 4; ++m) { f32x4 o;
; #pragma unroll
;                     for (int e = 0; e < 4; ++e) o[e] = yg[m][e] * __builtin_amdgcn_rcpf(1.0f + __expf(-yg[m][e])) * yv[m][e];
;                     *(unsigned long long*)(arow + (size_t)m * 2816) = (unsigned long long)cvt_pk_bf16(o[0], o[1]) | ((unsigned long long)cvt_pk_bf16(o[2], o[3]) << 32); }
	v_pk_fma_f32 v[36:37], v[20:21], v[72:73], v[36:37]
	v_pk_fma_f32 v[40:41], v[6:7], v[94:95], v[40:41]
	v_pk_fma_f32 v[36:37], v[12:13], v[68:69], v[36:37]
	v_pk_fma_f32 v[40:41], v[2:3], v[86:87], v[40:41]
	v_mov_b32_e32 v236, v248
	v_mov_b32_e32 v237, v249
	v_mov_b32_e32 v238, v34
	v_mov_b32_e32 v239, v35
	global_store_dwordx4 v[96:97], v[236:239], off
	v_mul_f32_e32 v32, v32, v38
	v_add_f32_e32 v34, 1.0, v39
	v_mul_f32_e32 v35, 0xbfb8aa3b, v40
	v_mul_f32_e32 v32, v36, v32
	v_rcp_f32_e32 v34, v34
	v_exp_f32_e32 v35, v35
	v_mul_f32_e32 v36, 0xbfb8aa3b, v41
	v_exp_f32_e32 v36, v36
	v_pk_fma_f32 v[50:51], v[4:5], v[76:77], v[88:89]
	v_mul_f32_e32 v33, v33, v34
	v_pk_fma_f32 v[50:51], v[0:1], v[92:93], v[50:51]
	v_add_f32_e32 v34, 1.0, v35
	v_pk_fma_f32 v[50:51], v[16:17], v[84:85], v[50:51]
	v_rcp_f32_e32 v34, v34
	v_add_f32_e32 v35, 1.0, v36
	v_rcp_f32_e32 v35, v35
	v_mul_f32_e32 v36, 0xbfb8aa3b, v50
	v_pk_fma_f32 v[44:45], v[66:67], v[44:45], v[82:83]
	v_exp_f32_e32 v36, v36
	v_pk_fma_f32 v[44:45], v[22:23], v[74:75], v[44:45]
	v_mul_f32_e32 v34, v40, v34
	v_pk_fma_f32 v[44:45], v[14:15], v[70:71], v[44:45]
	v_mul_f32_e32 v33, v37, v33
	v_mul_f32_e32 v34, v44, v34
	v_mul_f32_e32 v35, v41, v35
	v_mul_f32_e32 v35, v45, v35
	v_cvt_pk_bf16_f32 v32, v32, v33
	v_cvt_pk_bf16_f32 v33, v34, v35
	v_add_f32_e32 v34, 1.0, v36
	v_rcp_f32_e32 v34, v34
	v_mul_f32_e32 v35, 0xbfb8aa3b, v51
	v_pk_fma_f32 v[48:49], v[6:7], v[78:79], v[90:91]
	v_exp_f32_e32 v35, v35
	v_pk_fma_f32 v[48:49], v[2:3], v[94:95], v[48:49]
	v_mov_b32_e32 v236, v250
	v_mov_b32_e32 v237, v251
	v_mov_b32_e32 v238, v32
	v_mov_b32_e32 v239, v33
	global_store_dwordx4 v[98:99], v[236:239], off offset:1536
	v_pk_fma_f32 v[48:49], v[18:19], v[86:87], v[48:49]
	v_mul_f32_e32 v32, v50, v34
	v_mul_f32_e32 v34, 0xbfb8aa3b, v48
	v_add_f32_e32 v33, 1.0, v35
	v_exp_f32_e32 v34, v34
	v_mul_f32_e32 v35, 0xbfb8aa3b, v49
	v_exp_f32_e32 v35, v35
	v_pk_fma_f32 v[54:55], v[0:1], v[76:77], v[88:89]
	v_add_f32_e32 v34, 1.0, v34
	v_pk_fma_f32 v[54:55], v[16:17], v[92:93], v[54:55]
	v_rcp_f32_e32 v33, v33
	v_pk_fma_f32 v[54:55], v[8:9], v[84:85], v[54:55]
	v_rcp_f32_e32 v34, v34
	v_add_f32_e32 v35, 1.0, v35
	v_rcp_f32_e32 v35, v35
	v_mul_f32_e32 v36, 0xbfb8aa3b, v54
	v_pk_fma_f32 v[56:57], v[22:23], v[66:67], v[82:83]
	v_exp_f32_e32 v36, v36
	v_pk_fma_f32 v[56:57], v[14:15], v[74:75], v[56:57]
	v_pk_fma_f32 v[58:59], v[12:13], v[72:73], v[58:59]
	v_pk_fma_f32 v[56:57], v[30:31], v[70:71], v[56:57]
	v_pk_fma_f32 v[58:59], v[28:29], v[68:69], v[58:59]
	v_mul_f32_e32 v33, v51, v33
	v_mul_f32_e32 v34, v48, v34
	v_mul_f32_e32 v32, v58, v32
	v_mul_f32_e32 v33, v59, v33
	v_mul_f32_e32 v34, v56, v34
	v_mul_f32_e32 v35, v49, v35
	v_mul_f32_e32 v35, v57, v35
	v_cvt_pk_bf16_f32 v32, v32, v33
	v_cvt_pk_bf16_f32 v33, v34, v35
	v_add_f32_e32 v34, 1.0, v36
	v_rcp_f32_e32 v34, v34
	v_mul_f32_e32 v35, 0xbfb8aa3b, v55
	v_pk_fma_f32 v[52:53], v[2:3], v[78:79], v[90:91]
	v_exp_f32_e32 v35, v35
	v_pk_fma_f32 v[52:53], v[18:19], v[94:95], v[52:53]
	v_mov_b32_e32 v236, v252
	v_mov_b32_e32 v237, v253
	v_mov_b32_e32 v238, v32
	v_mov_b32_e32 v239, v33
	global_store_dwordx4 v[100:101], v[236:239], off offset:3072
	v_pk_fma_f32 v[52:53], v[10:11], v[86:87], v[52:53]
	v_mul_f32_e32 v32, v54, v34
	v_mul_f32_e32 v34, 0xbfb8aa3b, v52
	v_add_f32_e32 v33, 1.0, v35
	v_exp_f32_e32 v34, v34
	v_mul_f32_e32 v35, 0xbfb8aa3b, v53
	v_exp_f32_e32 v35, v35
	v_rcp_f32_e32 v33, v33
	v_add_f32_e32 v34, 1.0, v34
	v_rcp_f32_e32 v34, v34
	v_add_f32_e32 v35, 1.0, v35
	v_rcp_f32_e32 v35, v35
	v_pk_fma_f32 v[60:61], v[14:15], v[66:67], v[82:83]
	v_pk_fma_f32 v[62:63], v[28:29], v[72:73], v[62:63]
	v_pk_fma_f32 v[60:61], v[30:31], v[74:75], v[60:61]
	v_pk_fma_f32 v[62:63], v[24:25], v[68:69], v[62:63]
	v_pk_fma_f32 v[60:61], v[26:27], v[70:71], v[60:61]
	v_mul_f32_e32 v33, v55, v33
	v_mul_f32_e32 v34, v52, v34
	v_mul_f32_e32 v32, v62, v32
	v_mul_f32_e32 v33, v63, v33
	v_mul_f32_e32 v34, v60, v34
	v_mul_f32_e32 v35, v53, v35
	v_mul_f32_e32 v35, v61, v35
	v_cvt_pk_bf16_f32 v32, v32, v33
	v_cvt_pk_bf16_f32 v33, v34, v35
	v_add_co_u32_e32 v34, vcc, 0x4000, v96
	s_mov_b64 s[8:9], -1
	s_nop 0
	v_addc_co_u32_e32 v35, vcc, 0, v97, vcc
	v_cmp_gt_i32_e32 vcc, 15, v169
	v_mov_b32_e32 v236, v234
	v_mov_b32_e32 v237, v235
	v_mov_b32_e32 v238, v32
	v_mov_b32_e32 v239, v33
	global_store_dwordx4 v[34:35], v[236:239], off offset:512
	s_and_saveexec_b64 s[6:7], vcc
	s_cbranch_execz .LBB0_1333
	v_cmp_eq_u32_e32 vcc, 0, v169
	s_orn2_b64 s[8:9], vcc, exec
	s_or_b64 exec, exec, s[6:7]
	s_and_saveexec_b64 s[6:7], s[8:9]
	s_cbranch_execnz .LBB0_1334
